# late-needed transposes spread over idle tails: W_b at the end of P1 (184 idle blocks), W_out at the end of P4, W_q at the end of P5 (384 idle blocks each); P0 keeps only W_in and W_mem
# speedup vs baseline: 1.0135x; 1.0018x over previous
.LBB0_136:
	s_cmp_lt_u32 s2, 0x128
	s_cbranch_scc1 .Lta_done
	s_cmp_ge_u32 s2, 0x1e0
	s_cbranch_scc1 .Lta_done
	s_load_dwordx2 s[30:31], s[0:1], 0x40
	s_load_dwordx2 s[32:33], s[0:1], 0xb0
	s_load_dwordx2 s[34:35], s[0:1], 0xc8
	s_load_dwordx2 s[36:37], s[0:1], 0xd0
	s_load_dwordx2 s[38:39], s[0:1], 0xe0
	s_movk_i32 s3, 184
	v_lshrrev_b32_e32 v0, 4, v204
	v_and_b32_e32 v1, 15, v204
	v_lshlrev_b32_e32 v1, 4, v1
	v_lshrrev_b32_e32 v2, 3, v204
	v_and_b32_e32 v3, 7, v204
	v_add_u32_e32 v8, 0, v0
	v_mul_u32_u24_e32 v8, 0x104, v8
	v_add3_u32 v8, v8, v1, 32
	v_add_u32_e32 v72, 0x4100, v8
	v_add_u32_e32 v9, 16, v0
	v_mul_u32_u24_e32 v9, 0x104, v9
	v_add3_u32 v9, v9, v1, 32
	v_add_u32_e32 v73, 0x4100, v9
	v_add_u32_e32 v10, 32, v0
	v_mul_u32_u24_e32 v10, 0x104, v10
	v_add3_u32 v10, v10, v1, 32
	v_add_u32_e32 v74, 0x4100, v10
	v_add_u32_e32 v11, 48, v0
	v_mul_u32_u24_e32 v11, 0x104, v11
	v_add3_u32 v11, v11, v1, 32
	v_add_u32_e32 v75, 0x4100, v11
	v_mul_u32_u24_e32 v12, 0x820, v3
	v_lshl_add_u32 v12, v2, 2, v12
	v_add_u32_e32 v12, 32, v12
	v_add_u32_e32 v13, 0x410, v12
	v_add_u32_e32 v76, 0x4100, v12
	v_add_u32_e32 v77, 0x4100, v13
	v_lshlrev_b32_e32 v14, 12, v2
	v_lshl_add_u32 v14, v3, 4, v14
	v_add_u32_e32 v78, 0, v0
	v_add_u32_e32 v79, 16, v0
	v_add_u32_e32 v80, 32, v0
	v_add_u32_e32 v81, 48, v0
	s_waitcnt lgkmcnt(0)
	s_sub_u32 s4, s2, 0x128
	s_add_u32 s4, s4, 0x1700
	s_cmpk_ge_u32 s4, 0x1b00
	s_cbranch_scc1 .Lta_done
	s_mov_b32 s5, s4

.Lta_loop:
	s_add_u32 s18, s4, s3
	s_cmpk_lt_u32 s18, 0x1b00
	s_cselect_b32 s19, s18, s4
	s_mov_b32 s5, s19

.Lta_a_end:
	v_mad_u32_u24 v4, v78, s12, v1
	v_mad_u32_u24 v5, v79, s12, v1
	v_mad_u32_u24 v6, v80, s12, v1
	v_mad_u32_u24 v7, v81, s12, v1
	global_load_dwordx4 v[32:35], v4, s[10:11]
	global_load_dwordx4 v[36:39], v5, s[10:11]
	global_load_dwordx4 v[40:43], v6, s[10:11]
	global_load_dwordx4 v[44:47], v7, s[10:11]
	s_waitcnt vmcnt(4)
	ds_write2_b32 v8, v16, v17 offset1:1
	ds_write2_b32 v8, v18, v19 offset0:2 offset1:3
	ds_write2_b32 v9, v20, v21 offset1:1
	ds_write2_b32 v9, v22, v23 offset0:2 offset1:3
	ds_write2_b32 v10, v24, v25 offset1:1
	ds_write2_b32 v10, v26, v27 offset0:2 offset1:3
	ds_write2_b32 v11, v28, v29 offset1:1
	ds_write2_b32 v11, v30, v31 offset0:2 offset1:3
	v_and_b32_e32 v82, s27, v2
	v_xor_b32_e32 v82, s26, v82
	v_lshl_add_u32 v82, v82, 7, v14
	v_add_u32_e32 v83, 0x20000, v82
	s_waitcnt lgkmcnt(0)
	s_barrier
	ds_read2_b32 v[48:49], v12 offset1:65
	ds_read2_b32 v[50:51], v12 offset0:130 offset1:195
	ds_read2_b32 v[52:53], v13 offset1:65
	ds_read2_b32 v[54:55], v13 offset0:130 offset1:195
	ds_read2_b32 v[56:57], v12 offset0:32 offset1:97
	ds_read2_b32 v[58:59], v12 offset0:162 offset1:227
	ds_read2_b32 v[60:61], v13 offset0:32 offset1:97
	ds_read2_b32 v[62:63], v13 offset0:162 offset1:227
	s_waitcnt lgkmcnt(4)
	v_cvt_pk_bf16_f32 v64, v48, v49
	v_cvt_pk_bf16_f32 v65, v50, v51
	v_cvt_pk_bf16_f32 v66, v52, v53
	v_cvt_pk_bf16_f32 v67, v54, v55
	s_waitcnt lgkmcnt(0)
	v_cvt_pk_bf16_f32 v68, v56, v57
	v_cvt_pk_bf16_f32 v69, v58, v59
	v_cvt_pk_bf16_f32 v70, v60, v61
	v_cvt_pk_bf16_f32 v71, v62, v63
	global_store_dwordx4 v82, v[64:67], s[16:17]
	global_store_dwordx4 v83, v[68:71], s[16:17]
	s_mov_b64 s[16:17], s[14:15]
	s_mov_b32 s26, s6
	s_mov_b32 s27, s13
	s_mov_b32 s4, s18
	s_cmpk_lt_u32 s4, 0x1b00
	s_cbranch_scc0 .Lta_drain
	s_add_u32 s18, s4, s3
	s_cmpk_lt_u32 s18, 0x1b00
	s_cselect_b32 s19, s18, s4
	s_mov_b32 s5, s19

.Lta_b_end:
	v_mad_u32_u24 v4, v78, s12, v1
	v_mad_u32_u24 v5, v79, s12, v1
	v_mad_u32_u24 v6, v80, s12, v1
	v_mad_u32_u24 v7, v81, s12, v1
	global_load_dwordx4 v[16:19], v4, s[10:11]
	global_load_dwordx4 v[20:23], v5, s[10:11]
	global_load_dwordx4 v[24:27], v6, s[10:11]
	global_load_dwordx4 v[28:31], v7, s[10:11]
	s_waitcnt vmcnt(4)
	ds_write2_b32 v72, v32, v33 offset1:1
	ds_write2_b32 v72, v34, v35 offset0:2 offset1:3
	ds_write2_b32 v73, v36, v37 offset1:1
	ds_write2_b32 v73, v38, v39 offset0:2 offset1:3
	ds_write2_b32 v74, v40, v41 offset1:1
	ds_write2_b32 v74, v42, v43 offset0:2 offset1:3
	ds_write2_b32 v75, v44, v45 offset1:1
	ds_write2_b32 v75, v46, v47 offset0:2 offset1:3
	v_and_b32_e32 v82, s27, v2
	v_xor_b32_e32 v82, s26, v82
	v_lshl_add_u32 v82, v82, 7, v14
	v_add_u32_e32 v83, 0x20000, v82
	s_waitcnt lgkmcnt(0)
	s_barrier
	ds_read2_b32 v[48:49], v76 offset1:65
	ds_read2_b32 v[50:51], v76 offset0:130 offset1:195
	ds_read2_b32 v[52:53], v77 offset1:65
	ds_read2_b32 v[54:55], v77 offset0:130 offset1:195
	ds_read2_b32 v[56:57], v76 offset0:32 offset1:97
	ds_read2_b32 v[58:59], v76 offset0:162 offset1:227
	ds_read2_b32 v[60:61], v77 offset0:32 offset1:97
	ds_read2_b32 v[62:63], v77 offset0:162 offset1:227
	s_waitcnt lgkmcnt(4)
	v_cvt_pk_bf16_f32 v64, v48, v49
	v_cvt_pk_bf16_f32 v65, v50, v51
	v_cvt_pk_bf16_f32 v66, v52, v53
	v_cvt_pk_bf16_f32 v67, v54, v55
	s_waitcnt lgkmcnt(0)
	v_cvt_pk_bf16_f32 v68, v56, v57
	v_cvt_pk_bf16_f32 v69, v58, v59
	v_cvt_pk_bf16_f32 v70, v60, v61
	v_cvt_pk_bf16_f32 v71, v62, v63
	global_store_dwordx4 v82, v[64:67], s[16:17]
	global_store_dwordx4 v83, v[68:71], s[16:17]
	s_mov_b64 s[16:17], s[14:15]
	s_mov_b32 s26, s6
	s_mov_b32 s27, s13
	s_mov_b32 s4, s18
	s_cmpk_lt_u32 s4, 0x1b00
	s_cbranch_scc0 .Lta_drain
	s_branch .Lta_loop

.LBB0_658:
	s_cmp_lt_u32 s2, 0x80
	s_cbranch_scc1 .Ltb_done
	s_load_dwordx2 s[30:31], s[0:1], 0x40
	s_load_dwordx2 s[32:33], s[0:1], 0xb0
	s_load_dwordx2 s[34:35], s[0:1], 0xc8
	s_load_dwordx2 s[36:37], s[0:1], 0xd0
	s_load_dwordx2 s[38:39], s[0:1], 0xe0
	s_movk_i32 s3, 384
	v_lshrrev_b32_e32 v0, 4, v204
	v_and_b32_e32 v1, 15, v204
	v_lshlrev_b32_e32 v1, 4, v1
	v_lshrrev_b32_e32 v2, 3, v204
	v_and_b32_e32 v3, 7, v204
	v_add_u32_e32 v8, 0, v0
	v_mul_u32_u24_e32 v8, 0x104, v8
	v_add3_u32 v8, v8, v1, 32
	v_add_u32_e32 v72, 0x4100, v8
	v_add_u32_e32 v9, 16, v0
	v_mul_u32_u24_e32 v9, 0x104, v9
	v_add3_u32 v9, v9, v1, 32
	v_add_u32_e32 v73, 0x4100, v9
	v_add_u32_e32 v10, 32, v0
	v_mul_u32_u24_e32 v10, 0x104, v10
	v_add3_u32 v10, v10, v1, 32
	v_add_u32_e32 v74, 0x4100, v10
	v_add_u32_e32 v11, 48, v0
	v_mul_u32_u24_e32 v11, 0x104, v11
	v_add3_u32 v11, v11, v1, 32
	v_add_u32_e32 v75, 0x4100, v11
	v_mul_u32_u24_e32 v12, 0x820, v3
	v_lshl_add_u32 v12, v2, 2, v12
	v_add_u32_e32 v12, 32, v12
	v_add_u32_e32 v13, 0x410, v12
	v_add_u32_e32 v76, 0x4100, v12
	v_add_u32_e32 v77, 0x4100, v13
	v_lshlrev_b32_e32 v14, 12, v2
	v_lshl_add_u32 v14, v3, 4, v14
	v_add_u32_e32 v78, 0, v0
	v_add_u32_e32 v79, 16, v0
	v_add_u32_e32 v80, 32, v0
	v_add_u32_e32 v81, 48, v0
	s_waitcnt lgkmcnt(0)
	s_sub_u32 s4, s2, 0x80
	s_add_u32 s4, s4, 0x1b00
	s_cmpk_ge_u32 s4, 0x1f00
	s_cbranch_scc1 .Ltb_done
	s_mov_b32 s5, s4

.Ltb_loop:
	s_add_u32 s18, s4, s3
	s_cmpk_lt_u32 s18, 0x1f00
	s_cselect_b32 s19, s18, s4
	s_mov_b32 s5, s19

.Ltb_a_end:
	v_mad_u32_u24 v4, v78, s12, v1
	v_mad_u32_u24 v5, v79, s12, v1
	v_mad_u32_u24 v6, v80, s12, v1
	v_mad_u32_u24 v7, v81, s12, v1
	global_load_dwordx4 v[32:35], v4, s[10:11]
	global_load_dwordx4 v[36:39], v5, s[10:11]
	global_load_dwordx4 v[40:43], v6, s[10:11]
	global_load_dwordx4 v[44:47], v7, s[10:11]
	s_waitcnt vmcnt(4)
	ds_write2_b32 v8, v16, v17 offset1:1
	ds_write2_b32 v8, v18, v19 offset0:2 offset1:3
	ds_write2_b32 v9, v20, v21 offset1:1
	ds_write2_b32 v9, v22, v23 offset0:2 offset1:3
	ds_write2_b32 v10, v24, v25 offset1:1
	ds_write2_b32 v10, v26, v27 offset0:2 offset1:3
	ds_write2_b32 v11, v28, v29 offset1:1
	ds_write2_b32 v11, v30, v31 offset0:2 offset1:3
	v_and_b32_e32 v82, s27, v2
	v_xor_b32_e32 v82, s26, v82
	v_lshl_add_u32 v82, v82, 7, v14
	v_add_u32_e32 v83, 0x20000, v82
	s_waitcnt lgkmcnt(0)
	s_barrier
	ds_read2_b32 v[48:49], v12 offset1:65
	ds_read2_b32 v[50:51], v12 offset0:130 offset1:195
	ds_read2_b32 v[52:53], v13 offset1:65
	ds_read2_b32 v[54:55], v13 offset0:130 offset1:195
	ds_read2_b32 v[56:57], v12 offset0:32 offset1:97
	ds_read2_b32 v[58:59], v12 offset0:162 offset1:227
	ds_read2_b32 v[60:61], v13 offset0:32 offset1:97
	ds_read2_b32 v[62:63], v13 offset0:162 offset1:227
	s_waitcnt lgkmcnt(4)
	v_cvt_pk_bf16_f32 v64, v48, v49
	v_cvt_pk_bf16_f32 v65, v50, v51
	v_cvt_pk_bf16_f32 v66, v52, v53
	v_cvt_pk_bf16_f32 v67, v54, v55
	s_waitcnt lgkmcnt(0)
	v_cvt_pk_bf16_f32 v68, v56, v57
	v_cvt_pk_bf16_f32 v69, v58, v59
	v_cvt_pk_bf16_f32 v70, v60, v61
	v_cvt_pk_bf16_f32 v71, v62, v63
	global_store_dwordx4 v82, v[64:67], s[16:17]
	global_store_dwordx4 v83, v[68:71], s[16:17]
	s_mov_b64 s[16:17], s[14:15]
	s_mov_b32 s26, s6
	s_mov_b32 s27, s13
	s_mov_b32 s4, s18
	s_cmpk_lt_u32 s4, 0x1f00
	s_cbranch_scc0 .Ltb_drain
	s_add_u32 s18, s4, s3
	s_cmpk_lt_u32 s18, 0x1f00
	s_cselect_b32 s19, s18, s4
	s_mov_b32 s5, s19

.Ltb_b_end:
	v_mad_u32_u24 v4, v78, s12, v1
	v_mad_u32_u24 v5, v79, s12, v1
	v_mad_u32_u24 v6, v80, s12, v1
	v_mad_u32_u24 v7, v81, s12, v1
	global_load_dwordx4 v[16:19], v4, s[10:11]
	global_load_dwordx4 v[20:23], v5, s[10:11]
	global_load_dwordx4 v[24:27], v6, s[10:11]
	global_load_dwordx4 v[28:31], v7, s[10:11]
	s_waitcnt vmcnt(4)
	ds_write2_b32 v72, v32, v33 offset1:1
	ds_write2_b32 v72, v34, v35 offset0:2 offset1:3
	ds_write2_b32 v73, v36, v37 offset1:1
	ds_write2_b32 v73, v38, v39 offset0:2 offset1:3
	ds_write2_b32 v74, v40, v41 offset1:1
	ds_write2_b32 v74, v42, v43 offset0:2 offset1:3
	ds_write2_b32 v75, v44, v45 offset1:1
	ds_write2_b32 v75, v46, v47 offset0:2 offset1:3
	v_and_b32_e32 v82, s27, v2
	v_xor_b32_e32 v82, s26, v82
	v_lshl_add_u32 v82, v82, 7, v14
	v_add_u32_e32 v83, 0x20000, v82
	s_waitcnt lgkmcnt(0)
	s_barrier
	ds_read2_b32 v[48:49], v76 offset1:65
	ds_read2_b32 v[50:51], v76 offset0:130 offset1:195
	ds_read2_b32 v[52:53], v77 offset1:65
	ds_read2_b32 v[54:55], v77 offset0:130 offset1:195
	ds_read2_b32 v[56:57], v76 offset0:32 offset1:97
	ds_read2_b32 v[58:59], v76 offset0:162 offset1:227
	ds_read2_b32 v[60:61], v77 offset0:32 offset1:97
	ds_read2_b32 v[62:63], v77 offset0:162 offset1:227
	s_waitcnt lgkmcnt(4)
	v_cvt_pk_bf16_f32 v64, v48, v49
	v_cvt_pk_bf16_f32 v65, v50, v51
	v_cvt_pk_bf16_f32 v66, v52, v53
	v_cvt_pk_bf16_f32 v67, v54, v55
	s_waitcnt lgkmcnt(0)
	v_cvt_pk_bf16_f32 v68, v56, v57
	v_cvt_pk_bf16_f32 v69, v58, v59
	v_cvt_pk_bf16_f32 v70, v60, v61
	v_cvt_pk_bf16_f32 v71, v62, v63
	global_store_dwordx4 v82, v[64:67], s[16:17]
	global_store_dwordx4 v83, v[68:71], s[16:17]
	s_mov_b64 s[16:17], s[14:15]
	s_mov_b32 s26, s6
	s_mov_b32 s27, s13
	s_mov_b32 s4, s18
	s_cmpk_lt_u32 s4, 0x1f00
	s_cbranch_scc0 .Ltb_drain
	s_branch .Ltb_loop

.Ltb_done:
	s_load_dword s3, s[0:1], 0x120
	s_add_u32 s4, s0, 0x120
	s_addc_u32 s5, s1, 0
	s_waitcnt lgkmcnt(0)
	s_load_dwordx4 s[28:31], s[0:1], 0x110
	v_readlane_b32 s8, v244, 1
	v_readlane_b32 s9, v244, 2
	s_waitcnt lgkmcnt(0)
	s_cmp_lt_i32 s29, 6
	s_cselect_b64 s[6:7], -1, 0
	s_xor_b64 s[8:9], s[8:9], -1
	s_or_b64 s[6:7], s[6:7], s[8:9]
	s_and_b64 vcc, exec, s[6:7]
	s_cbranch_vccnz .LBB0_703
	s_waitcnt vmcnt(0)
	s_waitcnt vmcnt(63) expcnt(7) lgkmcnt(15)
	s_barrier
	s_and_saveexec_b64 s[6:7], s[56:57]
	s_cbranch_execz .LBB0_702
	v_readlane_b32 s8, v244, 0
	s_waitcnt vmcnt(0) expcnt(0) lgkmcnt(0)
	s_nop 0
	v_mov_b32_e32 v0, s8
	ds_read_b32 v2, v0
	ds_read_b32 v0, v0 offset:4
	s_waitcnt lgkmcnt(1)
	v_cmp_ne_u32_e32 vcc, 0, v2
	s_cbranch_vccnz .LBB0_673
	s_load_dwordx2 s[10:11], s[4:5], 0x4
	s_add_u32 s4, s58, 0x1000
	s_addc_u32 s5, s59, 0
	s_add_u32 s8, s58, 0x1100
	s_addc_u32 s9, s59, 0
	s_waitcnt lgkmcnt(0)
	s_mul_i32 s3, s10, s3
	s_add_u32 s10, s58, 0x1200
	s_mul_i32 s3, s3, s11
	s_addc_u32 s11, s59, 0
	s_add_u32 s12, s58, 0x1300
	s_addc_u32 s13, s59, 0
	s_mov_b32 s20, 1
	v_mov_b32_e32 v16, 0
	s_branch .LBB0_663

.LBB0_738:
	s_cmp_lt_u32 s2, 0x80
	s_cbranch_scc1 .Ltc_done
	s_load_dwordx2 s[30:31], s[0:1], 0x40
	s_load_dwordx2 s[32:33], s[0:1], 0xb0
	s_load_dwordx2 s[34:35], s[0:1], 0xc8
	s_load_dwordx2 s[36:37], s[0:1], 0xd0
	s_load_dwordx2 s[38:39], s[0:1], 0xe0
	s_movk_i32 s3, 384
	v_lshrrev_b32_e32 v0, 4, v204
	v_and_b32_e32 v1, 15, v204
	v_lshlrev_b32_e32 v1, 4, v1
	v_lshrrev_b32_e32 v2, 3, v204
	v_and_b32_e32 v3, 7, v204
	v_add_u32_e32 v8, 0, v0
	v_mul_u32_u24_e32 v8, 0x104, v8
	v_add3_u32 v8, v8, v1, 32
	v_add_u32_e32 v72, 0x4100, v8
	v_add_u32_e32 v9, 16, v0
	v_mul_u32_u24_e32 v9, 0x104, v9
	v_add3_u32 v9, v9, v1, 32
	v_add_u32_e32 v73, 0x4100, v9
	v_add_u32_e32 v10, 32, v0
	v_mul_u32_u24_e32 v10, 0x104, v10
	v_add3_u32 v10, v10, v1, 32
	v_add_u32_e32 v74, 0x4100, v10
	v_add_u32_e32 v11, 48, v0
	v_mul_u32_u24_e32 v11, 0x104, v11
	v_add3_u32 v11, v11, v1, 32
	v_add_u32_e32 v75, 0x4100, v11
	v_mul_u32_u24_e32 v12, 0x820, v3
	v_lshl_add_u32 v12, v2, 2, v12
	v_add_u32_e32 v12, 32, v12
	v_add_u32_e32 v13, 0x410, v12
	v_add_u32_e32 v76, 0x4100, v12
	v_add_u32_e32 v77, 0x4100, v13
	v_lshlrev_b32_e32 v14, 12, v2
	v_lshl_add_u32 v14, v3, 4, v14
	v_add_u32_e32 v78, 0, v0
	v_add_u32_e32 v79, 16, v0
	v_add_u32_e32 v80, 32, v0
	v_add_u32_e32 v81, 48, v0
	s_waitcnt lgkmcnt(0)
	s_sub_u32 s4, s2, 0x80
	s_add_u32 s4, s4, 0x1f00
	s_cmpk_ge_u32 s4, 0x2300
	s_cbranch_scc1 .Ltc_done
	s_mov_b32 s5, s4

.Ltc_done:
	s_load_dword s3, s[0:1], 0x120
	s_add_u32 s4, s0, 0x120
	s_addc_u32 s5, s1, 0
	s_waitcnt lgkmcnt(0)
	s_load_dwordx4 s[28:31], s[0:1], 0x110
	v_readlane_b32 s8, v244, 1
	v_readlane_b32 s9, v244, 2
	s_waitcnt lgkmcnt(0)
	s_cmp_lt_i32 s29, 7
	s_cselect_b64 s[6:7], -1, 0
	s_xor_b64 s[8:9], s[8:9], -1
	s_or_b64 s[6:7], s[6:7], s[8:9]
	s_and_b64 vcc, exec, s[6:7]
	s_cbranch_vccnz .LBB0_783
	s_waitcnt vmcnt(0)
	s_waitcnt vmcnt(63) expcnt(7) lgkmcnt(15)
	s_barrier
	s_and_saveexec_b64 s[6:7], s[56:57]
	s_cbranch_execz .LBB0_782
	v_readlane_b32 s8, v244, 0
	s_waitcnt vmcnt(0) expcnt(0) lgkmcnt(0)
	s_nop 0
	v_mov_b32_e32 v0, s8
	ds_read_b32 v2, v0
	ds_read_b32 v0, v0 offset:4
	s_waitcnt lgkmcnt(1)
	v_cmp_ne_u32_e32 vcc, 0, v2
	s_cbranch_vccnz .LBB0_753
	v_readlane_b32 s4, v244, 4
	v_readlane_b32 s5, v244, 5
	s_load_dwordx2 s[10:11], s[4:5], 0x4
	s_load_dword s3, s[0:1], 0x120
	s_add_u32 s4, s58, 0x1000
	s_addc_u32 s5, s59, 0
	s_add_u32 s8, s58, 0x1100
	s_addc_u32 s9, s59, 0
	s_waitcnt lgkmcnt(0)
	s_mul_i32 s3, s10, s3
	s_add_u32 s10, s58, 0x1200
	s_mul_i32 s3, s3, s11
	s_addc_u32 s11, s59, 0
	s_add_u32 s12, s58, 0x1300
	s_addc_u32 s13, s59, 0
	s_mov_b32 s20, 1
	v_mov_b32_e32 v16, 0
	s_branch .LBB0_743
